# v13 + P1: adaLN partial reduction distributed over the 8 waves (16 dependent load rounds per wave -> 1) and exchanged through LDS
# baseline (speedup 1.0000x reference)
; template <bool PARTIALS>
; __device__ __forceinline__ void norm_mod_phase(const float* X, const float* __restrict__ gain, const float* __restrict__ ada_b, const unsigned char* ws, int shift_off, int scale_off, bf16* H, int gw, int NGW, int lane) {
;     ...
;     for (int blk = gw; blk < T / 16; blk += NGW) {
;         const int r0 = blk * 16, b = r0 / SEQ;
;         f32x4 sc[4], sh[4];
; #pragma unroll
;         for (int j = 0; j < 4; ++j) {
;             const int c = 4 * lane + 256 * j;
;             f32x4 s, h;
;             if (PARTIALS) {
;                 s = *(const f32x4*)(ada_b + scale_off + c); h = *(const f32x4*)(ada_b + shift_off + c);
;                 for (int ks = 0; ks < KSPLIT; ++ks) { const float* p = adap + (size_t)(ks * 8 + b) * ADAW; s += *(const f32x4*)(p + scale_off + c); h += *(const f32x4*)(p + shift_off + c); }
;             } else { s = *(const f32x4*)(ada + (size_t)b * ADAW + scale_off + c); h = *(const f32x4*)(ada + (size_t)b * ADAW + shift_off + c); }
;             const f32x4 g = *(const f32x4*)(gain + c);
;             sc[j] = g * (s + 1.0f); sh[j] = h;
;         }
.LBB0_131:
	s_ashr_i32 s0, s33, 31
	s_lshr_b32 s0, s0, 24
	s_add_i32 s0, s33, s0
	s_ashr_i32 s0, s0, 8
	s_mul_hi_i32 s5, s0, 0x6000
	s_mul_i32 s4, s0, 0x6000
	v_readlane_b32 s6, v242, 17
	v_and_b32_e32 v138, 31, v96
	v_lshlrev_b32_e32 v138, 4, v138
	v_lshrrev_b32_e32 v139, 5, v96
	v_lshl_add_u32 v138, v139, 12, v138
	s_lshl_b32 s7, s6, 9
	v_add_u32_e32 v138, s7, v138
	v_readlane_b32 s0, v242, 26
	v_readlane_b32 s1, v242, 27
	s_nop 4
	global_load_dwordx4 v[140:143], v138, s[0:1]
	s_add_u32 s0, s28, s4
	s_addc_u32 s1, s29, s5
	s_add_u32 s0, s0, 0x2000000
	s_addc_u32 s1, s1, 0
	global_load_dwordx4 v[144:147], v138, s[0:1]
	s_add_u32 s0, s0, 0x30000
	s_addc_u32 s1, s1, 0
	global_load_dwordx4 v[148:151], v138, s[0:1]
	s_add_u32 s0, s0, 0x30000
	s_addc_u32 s1, s1, 0
	global_load_dwordx4 v[152:155], v138, s[0:1]
	s_add_u32 s0, s0, 0x30000
	s_addc_u32 s1, s1, 0
	global_load_dwordx4 v[156:159], v138, s[0:1]
	s_add_u32 s0, s0, 0x30000
	s_addc_u32 s1, s1, 0
	global_load_dwordx4 v[160:163], v138, s[0:1]
	s_add_u32 s0, s0, 0x30000
	s_addc_u32 s1, s1, 0
	global_load_dwordx4 v[164:167], v138, s[0:1]
	s_add_u32 s0, s0, 0x30000
	s_addc_u32 s1, s1, 0
	global_load_dwordx4 v[168:171], v138, s[0:1]
	s_add_u32 s0, s0, 0x30000
	s_addc_u32 s1, s1, 0
	global_load_dwordx4 v[172:175], v138, s[0:1]
	s_add_u32 s0, s0, 0x30000
	s_addc_u32 s1, s1, 0
	global_load_dwordx4 v[176:179], v138, s[0:1]
	s_add_u32 s0, s0, 0x30000
	s_addc_u32 s1, s1, 0
	global_load_dwordx4 v[180:183], v138, s[0:1]
	s_add_u32 s0, s0, 0x30000
	s_addc_u32 s1, s1, 0
	global_load_dwordx4 v[184:187], v138, s[0:1]
	s_add_u32 s0, s0, 0x30000
	s_addc_u32 s1, s1, 0
	global_load_dwordx4 v[188:191], v138, s[0:1]
	s_add_u32 s0, s0, 0x30000
	s_addc_u32 s1, s1, 0
	global_load_dwordx4 v[192:195], v138, s[0:1]
	s_add_u32 s0, s0, 0x30000
	s_addc_u32 s1, s1, 0
	global_load_dwordx4 v[196:199], v138, s[0:1]
	s_add_u32 s0, s0, 0x30000
	s_addc_u32 s1, s1, 0
	global_load_dwordx4 v[200:203], v138, s[0:1]
	s_add_u32 s0, s0, 0x30000
	s_addc_u32 s1, s1, 0
	global_load_dwordx4 v[204:207], v138, s[0:1]
	s_waitcnt vmcnt(15)
	v_pk_add_f32 v[140:141], v[140:141], v[144:145]
	v_pk_add_f32 v[142:143], v[142:143], v[146:147]
	s_waitcnt vmcnt(14)
	v_pk_add_f32 v[140:141], v[140:141], v[148:149]
	v_pk_add_f32 v[142:143], v[142:143], v[150:151]
	s_waitcnt vmcnt(13)
	v_pk_add_f32 v[140:141], v[140:141], v[152:153]
	v_pk_add_f32 v[142:143], v[142:143], v[154:155]
	s_waitcnt vmcnt(12)
	v_pk_add_f32 v[140:141], v[140:141], v[156:157]
	v_pk_add_f32 v[142:143], v[142:143], v[158:159]
	s_waitcnt vmcnt(11)
	v_pk_add_f32 v[140:141], v[140:141], v[160:161]
	v_pk_add_f32 v[142:143], v[142:143], v[162:163]
	s_waitcnt vmcnt(10)
	v_pk_add_f32 v[140:141], v[140:141], v[164:165]
	v_pk_add_f32 v[142:143], v[142:143], v[166:167]
	s_waitcnt vmcnt(9)
	v_pk_add_f32 v[140:141], v[140:141], v[168:169]
	v_pk_add_f32 v[142:143], v[142:143], v[170:171]
	s_waitcnt vmcnt(8)
	v_pk_add_f32 v[140:141], v[140:141], v[172:173]
	v_pk_add_f32 v[142:143], v[142:143], v[174:175]
	s_waitcnt vmcnt(7)
	v_pk_add_f32 v[140:141], v[140:141], v[176:177]
	v_pk_add_f32 v[142:143], v[142:143], v[178:179]
	s_waitcnt vmcnt(6)
	v_pk_add_f32 v[140:141], v[140:141], v[180:181]
	v_pk_add_f32 v[142:143], v[142:143], v[182:183]
	s_waitcnt vmcnt(5)
	v_pk_add_f32 v[140:141], v[140:141], v[184:185]
	v_pk_add_f32 v[142:143], v[142:143], v[186:187]
	s_waitcnt vmcnt(4)
	v_pk_add_f32 v[140:141], v[140:141], v[188:189]
	v_pk_add_f32 v[142:143], v[142:143], v[190:191]
	s_waitcnt vmcnt(3)
	v_pk_add_f32 v[140:141], v[140:141], v[192:193]
	v_pk_add_f32 v[142:143], v[142:143], v[194:195]
	s_waitcnt vmcnt(2)
	v_pk_add_f32 v[140:141], v[140:141], v[196:197]
	v_pk_add_f32 v[142:143], v[142:143], v[198:199]
	s_waitcnt vmcnt(1)
	v_pk_add_f32 v[140:141], v[140:141], v[200:201]
	v_pk_add_f32 v[142:143], v[142:143], v[202:203]
	s_waitcnt vmcnt(0)
	v_pk_add_f32 v[140:141], v[140:141], v[204:205]
	v_pk_add_f32 v[142:143], v[142:143], v[206:207]
	v_add_u32_e32 v139, 65536, v138
	ds_write_b128 v139, v[140:143]
	s_waitcnt lgkmcnt(0)
	s_barrier
	v_lshlrev_b32_e32 v139, 4, v96
	v_add_u32_e32 v139, 65536, v139
	ds_read_b128 v[48:51], v139
	ds_read_b128 v[52:55], v139 offset:1024
	ds_read_b128 v[56:59], v139 offset:2048
	ds_read_b128 v[64:67], v139 offset:3072
	ds_read_b128 v[60:63], v139 offset:4096
	ds_read_b128 v[68:71], v139 offset:5120
	ds_read_b128 v[72:75], v139 offset:6144
	ds_read_b128 v[92:95], v139 offset:7168
	s_waitcnt vmcnt(0) lgkmcnt(0)
	s_lshl_b32 s0, s33, 4
	s_ashr_i32 s1, s0, 31
	s_lshl_b64 s[4:5], s[0:1], 12
	v_lshl_add_u64 v[76:77], v[98:99], 0, s[4:5]
	global_load_dwordx4 v[80:83], v[76:77], off
	global_load_dwordx4 v[84:87], v[76:77], off offset:1024
	global_load_dwordx4 v[88:91], v[76:77], off offset:2048
	s_nop 0
	global_load_dwordx4 v[76:79], v[76:77], off offset:3072
	v_pk_add_f32 v[62:63], v[62:63], 1.0 op_sel_hi:[1,0]
	v_pk_add_f32 v[60:61], v[60:61], 1.0 op_sel_hi:[1,0]
	v_pk_mul_f32 v[120:121], v[10:11], v[62:63]
	v_pk_mul_f32 v[118:119], v[8:9], v[60:61]
	v_pk_add_f32 v[60:61], v[74:75], 1.0 op_sel_hi:[1,0]
	v_pk_add_f32 v[62:63], v[72:73], 1.0 op_sel_hi:[1,0]
	v_pk_add_f32 v[70:71], v[70:71], 1.0 op_sel_hi:[1,0]
	v_pk_add_f32 v[68:69], v[68:69], 1.0 op_sel_hi:[1,0]
	v_pk_mul_f32 v[112:113], v[42:43], v[60:61]
	v_pk_mul_f32 v[110:111], v[40:41], v[62:63]
	v_pk_add_f32 v[60:61], v[94:95], 1.0 op_sel_hi:[1,0]
	v_pk_add_f32 v[62:63], v[92:93], 1.0 op_sel_hi:[1,0]
	v_pk_mul_f32 v[116:117], v[14:15], v[70:71]
	v_pk_mul_f32 v[114:115], v[12:13], v[68:69]
	v_pk_mul_f32 v[94:95], v[46:47], v[60:61]
	v_pk_mul_f32 v[92:93], v[44:45], v[62:63]
	s_mov_b32 s1, 0
